# v75 + grid barrier: non-leader workgroups poll the cross-XCD release generation directly instead of waiting for their XCD leader to re-broadcast it (one hop less per barrier)
# baseline (speedup 1.0000x reference)
; __device__ __forceinline__ unsigned xb_ld(unsigned* p)              { return __hip_atomic_load(p, __ATOMIC_RELAXED, __HIP_MEMORY_SCOPE_AGENT); }
; __device__ __forceinline__ unsigned xb_add(unsigned* p, unsigned v) { return __hip_atomic_fetch_add(p, v, __ATOMIC_RELAXED, __HIP_MEMORY_SCOPE_AGENT); }
; #define XB_SPIN(cond, bar) do { unsigned _sp = 0; while (cond) { __builtin_amdgcn_s_sleep(1); \
;     if ((++_sp & 255u) == 0u) { if (xb_ld(&(bar)[XB_TMO])) break; if (_sp > XB_SPIN_CAP) { atomicAdd(&(bar)[XB_TMO], 1u); break; } } } } while (0)
; __device__ __forceinline__ void xcd_barrier(const XcdBarrier& b) {
;     ...
;         const unsigned old = xb_add(&bar[XB_XSUB(b.x)], 1u);
;         const unsigned gen = old / nloc;
;         if (old + 1u == (gen + 1u) * nloc) {
;             __builtin_amdgcn_fence(__ATOMIC_RELEASE, "agent");
;             asm volatile("s_waitcnt vmcnt(0)" ::: "memory");
;             const unsigned og = xb_add(&bar[XB_TOP], 1u);
;             const unsigned tg = og / nx;
;             if (og + 1u == (tg + 1u) * nx) xb_add(&bar[XB_TOPGEN], 1u);
;             else XB_SPIN(xb_ld(&bar[XB_TOPGEN]) == tg, bar);
;             __builtin_amdgcn_fence(__ATOMIC_ACQUIRE, "agent");
;             xb_add(&bar[XB_XGEN(b.x)], 1u);
;             asm volatile("s_waitcnt vmcnt(0)" ::: "memory");
;         } else {
;             XB_SPIN(xb_ld(&bar[XB_XGEN(b.x)]) == gen, bar);
.LBB0_143:
	s_or_b64 exec, exec, s[14:15]
	v_cvt_f32_u32_e32 v5, v3
	s_waitcnt vmcnt(0)
	v_readfirstlane_b32 s2, v4
	v_sub_u32_e32 v4, 0, v3
	v_rcp_iflag_f32_e32 v5, v5
	v_add_u32_e32 v6, s2, v0
	v_mul_f32_e32 v5, 0x4f7ffffe, v5
	v_cvt_u32_f32_e32 v5, v5
	v_mul_lo_u32 v0, v4, v5
	v_mul_hi_u32 v0, v5, v0
	v_add_u32_e32 v0, v5, v0
	v_mul_hi_u32 v0, v6, v0
	v_mul_lo_u32 v4, v0, v3
	v_sub_u32_e32 v4, v6, v4
	v_add_u32_e32 v5, 1, v0
	v_cmp_ge_u32_e32 vcc, v4, v3
	s_nop 1
	v_cndmask_b32_e32 v0, v0, v5, vcc
	v_sub_u32_e32 v5, v4, v3
	v_cndmask_b32_e32 v4, v4, v5, vcc
	v_add_u32_e32 v5, 1, v0
	v_cmp_ge_u32_e32 vcc, v4, v3
	v_add_u32_e32 v4, 1, v6
	s_nop 0
	v_cndmask_b32_e32 v0, v0, v5, vcc
	v_mul_lo_u32 v5, v3, v0
	v_add_u32_e32 v3, v5, v3
	v_cmp_ne_u32_e32 vcc, v4, v3
	s_and_saveexec_b64 s[2:3], vcc
	s_xor_b64 s[14:15], exec, s[2:3]
	s_cbranch_execz .LBB0_157
	v_readlane_b32 s2, v254, 1
	v_readlane_b32 s3, v254, 2
	s_waitcnt lgkmcnt(0)
	s_nop 3
	global_load_dword v2, v1, s[2:3] sc1
	s_waitcnt vmcnt(0)
	v_cmp_eq_u32_e32 vcc, v2, v0
	s_and_saveexec_b64 s[20:21], vcc
	s_cbranch_execz .LBB0_156
	s_mov_b32 s2, 1
	s_mov_b64 s[28:29], 0
	s_branch .LBB0_147

; __device__ __forceinline__ unsigned xb_ld(unsigned* p)              { return __hip_atomic_load(p, __ATOMIC_RELAXED, __HIP_MEMORY_SCOPE_AGENT); }
; __device__ __forceinline__ unsigned xb_add(unsigned* p, unsigned v) { return __hip_atomic_fetch_add(p, v, __ATOMIC_RELAXED, __HIP_MEMORY_SCOPE_AGENT); }
; #define XB_SPIN(cond, bar) do { unsigned _sp = 0; while (cond) { __builtin_amdgcn_s_sleep(1); \
;     if ((++_sp & 255u) == 0u) { if (xb_ld(&(bar)[XB_TMO])) break; if (_sp > XB_SPIN_CAP) { atomicAdd(&(bar)[XB_TMO], 1u); break; } } } } while (0)
; __device__ __forceinline__ void xcd_barrier(const XcdBarrier& b) {
;     ...
;         const unsigned old = xb_add(&bar[XB_XSUB(b.x)], 1u);
;         const unsigned gen = old / nloc;
;         if (old + 1u == (gen + 1u) * nloc) {
;             __builtin_amdgcn_fence(__ATOMIC_RELEASE, "agent");
;             asm volatile("s_waitcnt vmcnt(0)" ::: "memory");
;             const unsigned og = xb_add(&bar[XB_TOP], 1u);
;             const unsigned tg = og / nx;
;             if (og + 1u == (tg + 1u) * nx) xb_add(&bar[XB_TOPGEN], 1u);
;             else XB_SPIN(xb_ld(&bar[XB_TOPGEN]) == tg, bar);
;             __builtin_amdgcn_fence(__ATOMIC_ACQUIRE, "agent");
;             xb_add(&bar[XB_XGEN(b.x)], 1u);
;             asm volatile("s_waitcnt vmcnt(0)" ::: "memory");
;         } else {
;             XB_SPIN(xb_ld(&bar[XB_XGEN(b.x)]) == gen, bar);
.LBB0_408:
	s_or_b64 exec, exec, s[10:11]
	v_cvt_f32_u32_e32 v5, v3
	s_waitcnt vmcnt(0)
	v_readfirstlane_b32 s2, v4
	v_sub_u32_e32 v4, 0, v3
	v_rcp_iflag_f32_e32 v5, v5
	v_add_u32_e32 v6, s2, v0
	v_mul_f32_e32 v5, 0x4f7ffffe, v5
	v_cvt_u32_f32_e32 v5, v5
	v_mul_lo_u32 v0, v4, v5
	v_mul_hi_u32 v0, v5, v0
	v_add_u32_e32 v0, v5, v0
	v_mul_hi_u32 v0, v6, v0
	v_mul_lo_u32 v4, v0, v3
	v_sub_u32_e32 v4, v6, v4
	v_add_u32_e32 v5, 1, v0
	v_cmp_ge_u32_e32 vcc, v4, v3
	s_nop 1
	v_cndmask_b32_e32 v0, v0, v5, vcc
	v_sub_u32_e32 v5, v4, v3
	v_cndmask_b32_e32 v4, v4, v5, vcc
	v_add_u32_e32 v5, 1, v0
	v_cmp_ge_u32_e32 vcc, v4, v3
	v_add_u32_e32 v4, 1, v6
	s_nop 0
	v_cndmask_b32_e32 v0, v0, v5, vcc
	v_mul_lo_u32 v5, v3, v0
	v_add_u32_e32 v3, v5, v3
	v_cmp_ne_u32_e32 vcc, v4, v3
	s_and_saveexec_b64 s[2:3], vcc
	s_xor_b64 s[10:11], exec, s[2:3]
	s_cbranch_execz .LBB0_422
	v_readlane_b32 s2, v254, 1
	v_readlane_b32 s3, v254, 2
	s_waitcnt lgkmcnt(0)
	s_nop 3
	global_load_dword v2, v1, s[2:3] sc1
	s_waitcnt vmcnt(0)
	v_cmp_eq_u32_e32 vcc, v2, v0
	s_and_saveexec_b64 s[14:15], vcc
	s_cbranch_execz .LBB0_421
	s_mov_b32 s2, 1
	s_mov_b64 s[20:21], 0
	s_branch .LBB0_412

; __device__ __forceinline__ unsigned xb_ld(unsigned* p)              { return __hip_atomic_load(p, __ATOMIC_RELAXED, __HIP_MEMORY_SCOPE_AGENT); }
; __device__ __forceinline__ unsigned xb_add(unsigned* p, unsigned v) { return __hip_atomic_fetch_add(p, v, __ATOMIC_RELAXED, __HIP_MEMORY_SCOPE_AGENT); }
; #define XB_SPIN(cond, bar) do { unsigned _sp = 0; while (cond) { __builtin_amdgcn_s_sleep(1); \
;     if ((++_sp & 255u) == 0u) { if (xb_ld(&(bar)[XB_TMO])) break; if (_sp > XB_SPIN_CAP) { atomicAdd(&(bar)[XB_TMO], 1u); break; } } } } while (0)
; __device__ __forceinline__ void xcd_barrier(const XcdBarrier& b) {
;     ...
;         const unsigned old = xb_add(&bar[XB_XSUB(b.x)], 1u);
;         const unsigned gen = old / nloc;
;         if (old + 1u == (gen + 1u) * nloc) {
;             __builtin_amdgcn_fence(__ATOMIC_RELEASE, "agent");
;             asm volatile("s_waitcnt vmcnt(0)" ::: "memory");
;             const unsigned og = xb_add(&bar[XB_TOP], 1u);
;             const unsigned tg = og / nx;
;             if (og + 1u == (tg + 1u) * nx) xb_add(&bar[XB_TOPGEN], 1u);
;             else XB_SPIN(xb_ld(&bar[XB_TOPGEN]) == tg, bar);
;             __builtin_amdgcn_fence(__ATOMIC_ACQUIRE, "agent");
;             xb_add(&bar[XB_XGEN(b.x)], 1u);
;             asm volatile("s_waitcnt vmcnt(0)" ::: "memory");
;         } else {
;             XB_SPIN(xb_ld(&bar[XB_XGEN(b.x)]) == gen, bar);
.LBB0_629:
	s_or_b64 exec, exec, s[8:9]
	v_cvt_f32_u32_e32 v5, v3
	s_waitcnt vmcnt(0)
	v_readfirstlane_b32 s2, v4
	v_sub_u32_e32 v4, 0, v3
	v_rcp_iflag_f32_e32 v5, v5
	v_add_u32_e32 v6, s2, v0
	v_mul_f32_e32 v5, 0x4f7ffffe, v5
	v_cvt_u32_f32_e32 v5, v5
	v_mul_lo_u32 v0, v4, v5
	v_mul_hi_u32 v0, v5, v0
	v_add_u32_e32 v0, v5, v0
	v_mul_hi_u32 v0, v6, v0
	v_mul_lo_u32 v4, v0, v3
	v_sub_u32_e32 v4, v6, v4
	v_add_u32_e32 v5, 1, v0
	v_cmp_ge_u32_e32 vcc, v4, v3
	s_nop 1
	v_cndmask_b32_e32 v0, v0, v5, vcc
	v_sub_u32_e32 v5, v4, v3
	v_cndmask_b32_e32 v4, v4, v5, vcc
	v_add_u32_e32 v5, 1, v0
	v_cmp_ge_u32_e32 vcc, v4, v3
	v_add_u32_e32 v4, 1, v6
	s_nop 0
	v_cndmask_b32_e32 v0, v0, v5, vcc
	v_mul_lo_u32 v5, v3, v0
	v_add_u32_e32 v3, v5, v3
	v_cmp_ne_u32_e32 vcc, v4, v3
	s_and_saveexec_b64 s[2:3], vcc
	s_xor_b64 s[8:9], exec, s[2:3]
	s_cbranch_execz .LBB0_643
	v_readlane_b32 s2, v254, 1
	v_readlane_b32 s3, v254, 2
	s_waitcnt lgkmcnt(0)
	s_nop 3
	global_load_dword v2, v1, s[2:3] sc1
	s_waitcnt vmcnt(0)
	v_cmp_eq_u32_e32 vcc, v2, v0
	s_and_saveexec_b64 s[10:11], vcc
	s_cbranch_execz .LBB0_642
	s_mov_b32 s2, 1
	s_mov_b64 s[14:15], 0
	s_branch .LBB0_633
